# grid barrier: member workgroups poll the top-level generation word directly (one device-scope hop less per sync) on top of phase-0 balance
# speedup vs baseline: 1.0053x; 1.0029x over previous
; __device__ __forceinline__ unsigned xb_ld(unsigned* p)              { return __hip_atomic_load(p, __ATOMIC_RELAXED, __HIP_MEMORY_SCOPE_AGENT); }
; __device__ __forceinline__ unsigned xb_add(unsigned* p, unsigned v) { return __hip_atomic_fetch_add(p, v, __ATOMIC_RELAXED, __HIP_MEMORY_SCOPE_AGENT); }
; #define XB_SPIN(cond, bar) do { unsigned _sp = 0; while (cond) { __builtin_amdgcn_s_sleep(1); \
;     if ((++_sp & 255u) == 0u) { if (xb_ld(&(bar)[XB_TMO])) break; if (_sp > XB_SPIN_CAP) { atomicAdd(&(bar)[XB_TMO], 1u); break; } } } } while (0)
; __device__ __forceinline__ void xcd_barrier(const XcdBarrier& b) {
;     ...
;         const unsigned old = xb_add(&bar[XB_XSUB(b.x)], 1u);
;         const unsigned gen = old / nloc;
;         if (old + 1u == (gen + 1u) * nloc) {
;             __builtin_amdgcn_fence(__ATOMIC_RELEASE, "agent");
;             asm volatile("s_waitcnt vmcnt(0)" ::: "memory");
;             const unsigned og = xb_add(&bar[XB_TOP], 1u);
;             const unsigned tg = og / nx;
;             if (og + 1u == (tg + 1u) * nx) xb_add(&bar[XB_TOPGEN], 1u);
;             else XB_SPIN(xb_ld(&bar[XB_TOPGEN]) == tg, bar);
;             __builtin_amdgcn_fence(__ATOMIC_ACQUIRE, "agent");
;             xb_add(&bar[XB_XGEN(b.x)], 1u);
;             asm volatile("s_waitcnt vmcnt(0)" ::: "memory");
;         } else {
;             XB_SPIN(xb_ld(&bar[XB_XGEN(b.x)]) == gen, bar);
.LBB0_93:
	s_or_b64 exec, exec, s[10:11]
	v_cvt_f32_u32_e32 v4, v2
	s_waitcnt vmcnt(0)
	v_readfirstlane_b32 s2, v3
	v_sub_u32_e32 v3, 0, v2
	v_rcp_iflag_f32_e32 v4, v4
	v_add_u32_e32 v5, s2, v0
	v_mul_f32_e32 v4, 0x4f7ffffe, v4
	v_cvt_u32_f32_e32 v4, v4
	v_mul_lo_u32 v0, v3, v4
	v_mul_hi_u32 v0, v4, v0
	v_add_u32_e32 v0, v4, v0
	v_mul_hi_u32 v0, v5, v0
	v_mul_lo_u32 v3, v0, v2
	v_sub_u32_e32 v3, v5, v3
	v_add_u32_e32 v4, 1, v0
	v_cmp_ge_u32_e32 vcc, v3, v2
	s_nop 1
	v_cndmask_b32_e32 v0, v0, v4, vcc
	v_sub_u32_e32 v4, v3, v2
	v_cndmask_b32_e32 v3, v3, v4, vcc
	v_add_u32_e32 v4, 1, v0
	v_cmp_ge_u32_e32 vcc, v3, v2
	v_add_u32_e32 v3, 1, v5
	s_nop 0
	v_cndmask_b32_e32 v0, v0, v4, vcc
	v_mul_lo_u32 v4, v2, v0
	v_add_u32_e32 v2, v4, v2
	v_cmp_ne_u32_e32 vcc, v3, v2
	s_and_saveexec_b64 s[6:7], vcc
	s_xor_b64 s[8:9], exec, s[6:7]
	s_cbranch_execz .LBB0_107
	s_waitcnt lgkmcnt(0)
	v_mov_b32_e32 v1, 0x2000
	s_add_u32 s14, s26, 0x2c60b500
	s_addc_u32 s15, s27, 0
	v_mov_b32_e32 v1, 0
	global_load_dword v1, v1, s[14:15] sc1
	s_waitcnt vmcnt(0)
	v_cmp_eq_u32_e32 vcc, v1, v0
	s_and_saveexec_b64 s[10:11], vcc
	s_cbranch_execz .LBB0_106
	s_add_u32 s12, s26, 0x2c608200
	s_addc_u32 s13, s27, 0
	s_mov_b32 s2, 1
	s_mov_b64 s[16:17], 0
	v_mov_b32_e32 v1, 0
	s_branch .LBB0_97

; __device__ __forceinline__ unsigned xb_ld(unsigned* p)              { return __hip_atomic_load(p, __ATOMIC_RELAXED, __HIP_MEMORY_SCOPE_AGENT); }
; __device__ __forceinline__ unsigned xb_add(unsigned* p, unsigned v) { return __hip_atomic_fetch_add(p, v, __ATOMIC_RELAXED, __HIP_MEMORY_SCOPE_AGENT); }
; #define XB_SPIN(cond, bar) do { unsigned _sp = 0; while (cond) { __builtin_amdgcn_s_sleep(1); \
;     if ((++_sp & 255u) == 0u) { if (xb_ld(&(bar)[XB_TMO])) break; if (_sp > XB_SPIN_CAP) { atomicAdd(&(bar)[XB_TMO], 1u); break; } } } } while (0)
; __device__ __forceinline__ void xcd_barrier(const XcdBarrier& b) {
;     ...
;         const unsigned old = xb_add(&bar[XB_XSUB(b.x)], 1u);
;         const unsigned gen = old / nloc;
;         if (old + 1u == (gen + 1u) * nloc) {
;             __builtin_amdgcn_fence(__ATOMIC_RELEASE, "agent");
;             asm volatile("s_waitcnt vmcnt(0)" ::: "memory");
;             const unsigned og = xb_add(&bar[XB_TOP], 1u);
;             const unsigned tg = og / nx;
;             if (og + 1u == (tg + 1u) * nx) xb_add(&bar[XB_TOPGEN], 1u);
;             else XB_SPIN(xb_ld(&bar[XB_TOPGEN]) == tg, bar);
;             __builtin_amdgcn_fence(__ATOMIC_ACQUIRE, "agent");
;             xb_add(&bar[XB_XGEN(b.x)], 1u);
;             asm volatile("s_waitcnt vmcnt(0)" ::: "memory");
;         } else {
;             XB_SPIN(xb_ld(&bar[XB_XGEN(b.x)]) == gen, bar);
.LBB0_216:
	s_or_b64 exec, exec, s[12:13]
	v_cvt_f32_u32_e32 v4, v2
	s_waitcnt vmcnt(0)
	v_readfirstlane_b32 s2, v3
	v_sub_u32_e32 v3, 0, v2
	v_rcp_iflag_f32_e32 v4, v4
	v_add_u32_e32 v5, s2, v0
	v_mul_f32_e32 v4, 0x4f7ffffe, v4
	v_cvt_u32_f32_e32 v4, v4
	v_mul_lo_u32 v0, v3, v4
	v_mul_hi_u32 v0, v4, v0
	v_add_u32_e32 v0, v4, v0
	v_mul_hi_u32 v0, v5, v0
	v_mul_lo_u32 v3, v0, v2
	v_sub_u32_e32 v3, v5, v3
	v_add_u32_e32 v4, 1, v0
	v_cmp_ge_u32_e32 vcc, v3, v2
	s_nop 1
	v_cndmask_b32_e32 v0, v0, v4, vcc
	v_sub_u32_e32 v4, v3, v2
	v_cndmask_b32_e32 v3, v3, v4, vcc
	v_add_u32_e32 v4, 1, v0
	v_cmp_ge_u32_e32 vcc, v3, v2
	v_add_u32_e32 v3, 1, v5
	s_nop 0
	v_cndmask_b32_e32 v0, v0, v4, vcc
	v_mul_lo_u32 v4, v2, v0
	v_add_u32_e32 v2, v4, v2
	v_cmp_ne_u32_e32 vcc, v3, v2
	s_and_saveexec_b64 s[6:7], vcc
	s_xor_b64 s[8:9], exec, s[6:7]
	s_cbranch_execz .LBB0_230
	s_waitcnt lgkmcnt(0)
	v_mov_b32_e32 v1, 0x2000
	s_add_u32 s16, s26, 0x2c60b500
	s_addc_u32 s17, s27, 0
	v_mov_b32_e32 v1, 0
	global_load_dword v1, v1, s[16:17] sc1
	s_waitcnt vmcnt(0)
	v_cmp_eq_u32_e32 vcc, v1, v0
	s_and_saveexec_b64 s[12:13], vcc
	s_cbranch_execz .LBB0_229
	s_add_u32 s14, s26, 0x2c608200
	s_addc_u32 s15, s27, 0
	s_mov_b32 s2, 1
	s_mov_b64 s[18:19], 0
	v_mov_b32_e32 v1, 0
	s_branch .LBB0_220

; __device__ __forceinline__ unsigned xb_ld(unsigned* p)              { return __hip_atomic_load(p, __ATOMIC_RELAXED, __HIP_MEMORY_SCOPE_AGENT); }
; __device__ __forceinline__ unsigned xb_add(unsigned* p, unsigned v) { return __hip_atomic_fetch_add(p, v, __ATOMIC_RELAXED, __HIP_MEMORY_SCOPE_AGENT); }
; #define XB_SPIN(cond, bar) do { unsigned _sp = 0; while (cond) { __builtin_amdgcn_s_sleep(1); \
;     if ((++_sp & 255u) == 0u) { if (xb_ld(&(bar)[XB_TMO])) break; if (_sp > XB_SPIN_CAP) { atomicAdd(&(bar)[XB_TMO], 1u); break; } } } } while (0)
; __device__ __forceinline__ void xcd_barrier(const XcdBarrier& b) {
;     ...
;         const unsigned old = xb_add(&bar[XB_XSUB(b.x)], 1u);
;         const unsigned gen = old / nloc;
;         if (old + 1u == (gen + 1u) * nloc) {
;             __builtin_amdgcn_fence(__ATOMIC_RELEASE, "agent");
;             asm volatile("s_waitcnt vmcnt(0)" ::: "memory");
;             const unsigned og = xb_add(&bar[XB_TOP], 1u);
;             const unsigned tg = og / nx;
;             if (og + 1u == (tg + 1u) * nx) xb_add(&bar[XB_TOPGEN], 1u);
;             else XB_SPIN(xb_ld(&bar[XB_TOPGEN]) == tg, bar);
;             __builtin_amdgcn_fence(__ATOMIC_ACQUIRE, "agent");
;             xb_add(&bar[XB_XGEN(b.x)], 1u);
;             asm volatile("s_waitcnt vmcnt(0)" ::: "memory");
;         } else {
;             XB_SPIN(xb_ld(&bar[XB_XGEN(b.x)]) == gen, bar);
.LBB0_298:
	s_or_b64 exec, exec, s[14:15]
	v_cvt_f32_u32_e32 v4, v2
	s_waitcnt vmcnt(0)
	v_readfirstlane_b32 s2, v3
	v_sub_u32_e32 v3, 0, v2
	s_lshl_b32 s4, s33, 6
	v_rcp_iflag_f32_e32 v4, v4
	v_add_u32_e32 v5, s2, v0
	v_mul_f32_e32 v4, 0x4f7ffffe, v4
	v_cvt_u32_f32_e32 v4, v4
	v_mul_lo_u32 v0, v3, v4
	v_mul_hi_u32 v0, v4, v0
	v_add_u32_e32 v0, v4, v0
	v_mul_hi_u32 v0, v5, v0
	v_mul_lo_u32 v3, v0, v2
	v_sub_u32_e32 v3, v5, v3
	v_add_u32_e32 v4, 1, v0
	v_cmp_ge_u32_e32 vcc, v3, v2
	s_nop 1
	v_cndmask_b32_e32 v0, v0, v4, vcc
	v_sub_u32_e32 v4, v3, v2
	v_cndmask_b32_e32 v3, v3, v4, vcc
	v_add_u32_e32 v4, 1, v0
	v_cmp_ge_u32_e32 vcc, v3, v2
	v_add_u32_e32 v3, 1, v5
	s_nop 0
	v_cndmask_b32_e32 v0, v0, v4, vcc
	v_mul_lo_u32 v4, v2, v0
	v_add_u32_e32 v2, v4, v2
	v_cmp_ne_u32_e32 vcc, v3, v2
	s_and_saveexec_b64 s[6:7], vcc
	s_xor_b64 s[12:13], exec, s[6:7]
	s_cbranch_execz .LBB0_312
	s_waitcnt lgkmcnt(0)
	v_mov_b32_e32 v1, 0x2000
	s_add_u32 s18, s26, 0x2c60b500
	s_addc_u32 s19, s27, 0
	v_mov_b32_e32 v1, 0
	global_load_dword v1, v1, s[18:19] sc1
	s_waitcnt vmcnt(0)
	v_cmp_eq_u32_e32 vcc, v1, v0
	s_and_saveexec_b64 s[14:15], vcc
	s_cbranch_execz .LBB0_311
	s_add_u32 s16, s26, 0x2c608200
	s_addc_u32 s17, s27, 0
	s_mov_b32 s2, 1
	s_mov_b64 s[34:35], 0
	v_mov_b32_e32 v1, 0
	s_branch .LBB0_302

; __device__ __forceinline__ unsigned xb_ld(unsigned* p)              { return __hip_atomic_load(p, __ATOMIC_RELAXED, __HIP_MEMORY_SCOPE_AGENT); }
; __device__ __forceinline__ unsigned xb_add(unsigned* p, unsigned v) { return __hip_atomic_fetch_add(p, v, __ATOMIC_RELAXED, __HIP_MEMORY_SCOPE_AGENT); }
; #define XB_SPIN(cond, bar) do { unsigned _sp = 0; while (cond) { __builtin_amdgcn_s_sleep(1); \
;     if ((++_sp & 255u) == 0u) { if (xb_ld(&(bar)[XB_TMO])) break; if (_sp > XB_SPIN_CAP) { atomicAdd(&(bar)[XB_TMO], 1u); break; } } } } while (0)
; __device__ __forceinline__ void xcd_barrier(const XcdBarrier& b) {
;     ...
;         const unsigned old = xb_add(&bar[XB_XSUB(b.x)], 1u);
;         const unsigned gen = old / nloc;
;         if (old + 1u == (gen + 1u) * nloc) {
;             __builtin_amdgcn_fence(__ATOMIC_RELEASE, "agent");
;             asm volatile("s_waitcnt vmcnt(0)" ::: "memory");
;             const unsigned og = xb_add(&bar[XB_TOP], 1u);
;             const unsigned tg = og / nx;
;             if (og + 1u == (tg + 1u) * nx) xb_add(&bar[XB_TOPGEN], 1u);
;             else XB_SPIN(xb_ld(&bar[XB_TOPGEN]) == tg, bar);
;             __builtin_amdgcn_fence(__ATOMIC_ACQUIRE, "agent");
;             xb_add(&bar[XB_XGEN(b.x)], 1u);
;             asm volatile("s_waitcnt vmcnt(0)" ::: "memory");
;         } else {
;             XB_SPIN(xb_ld(&bar[XB_XGEN(b.x)]) == gen, bar);
.LBB0_352:
	v_mov_b32_e32 v1, 1
	global_atomic_add v3, v[186:187], v1, off sc0
	v_cvt_f32_u32_e32 v1, v2
	v_sub_u32_e32 v4, 0, v2
	v_rcp_iflag_f32_e32 v1, v1
	s_nop 0
	v_mul_f32_e32 v1, 0x4f7ffffe, v1
	v_cvt_u32_f32_e32 v1, v1
	v_mul_lo_u32 v4, v4, v1
	v_mul_hi_u32 v4, v1, v4
	v_add_u32_e32 v1, v1, v4
	s_waitcnt vmcnt(0)
	v_mul_hi_u32 v1, v3, v1
	v_mul_lo_u32 v4, v1, v2
	v_sub_u32_e32 v4, v3, v4
	v_add_u32_e32 v5, 1, v1
	v_cmp_ge_u32_e32 vcc, v4, v2
	v_add_u32_e32 v3, 1, v3
	s_nop 0
	v_cndmask_b32_e32 v1, v1, v5, vcc
	v_sub_u32_e32 v5, v4, v2
	v_cndmask_b32_e32 v4, v4, v5, vcc
	v_add_u32_e32 v5, 1, v1
	v_cmp_ge_u32_e32 vcc, v4, v2
	s_nop 1
	v_cndmask_b32_e32 v1, v1, v5, vcc
	v_mul_lo_u32 v4, v2, v1
	v_add_u32_e32 v2, v4, v2
	v_cmp_ne_u32_e32 vcc, v3, v2
	s_and_saveexec_b64 s[2:3], vcc
	s_xor_b64 s[4:5], exec, s[2:3]
	s_cbranch_execz .LBB0_366
	s_waitcnt lgkmcnt(0)
	v_mov_b32_e32 v0, 0
	global_load_dword v0, v0, s[92:93] sc1
	s_waitcnt vmcnt(0)
	v_cmp_eq_u32_e32 vcc, v0, v1
	s_and_saveexec_b64 s[8:9], vcc
	s_cbranch_execz .LBB0_365
	s_mov_b32 s2, 1
	s_mov_b64 s[12:13], 0
	v_mov_b32_e32 v0, 0
	s_branch .LBB0_356

; __device__ __forceinline__ unsigned xb_ld(unsigned* p)              { return __hip_atomic_load(p, __ATOMIC_RELAXED, __HIP_MEMORY_SCOPE_AGENT); }
; #define XB_SPIN(cond, bar) do { unsigned _sp = 0; while (cond) { __builtin_amdgcn_s_sleep(1); \
;     if ((++_sp & 255u) == 0u) { if (xb_ld(&(bar)[XB_TMO])) break; if (_sp > XB_SPIN_CAP) { atomicAdd(&(bar)[XB_TMO], 1u); break; } } } } while (0)
; __device__ __forceinline__ void xcd_barrier(const XcdBarrier& b) {
;     ...
;             XB_SPIN(xb_ld(&bar[XB_XGEN(b.x)]) == gen, bar);
.LBB0_360:
	global_load_dword v2, v0, s[92:93] sc1
	s_add_i32 s2, s2, 1
	s_mov_b64 s[20:21], -1
	s_waitcnt vmcnt(0)
	v_cmp_ne_u32_e32 vcc, v2, v1
	s_orn2_b64 s[16:17], vcc, exec
	s_branch .LBB0_355

; __device__ __forceinline__ unsigned xb_ld(unsigned* p)              { return __hip_atomic_load(p, __ATOMIC_RELAXED, __HIP_MEMORY_SCOPE_AGENT); }
; #define XB_SPIN(cond, bar) do { unsigned _sp = 0; while (cond) { __builtin_amdgcn_s_sleep(1); \
;     if ((++_sp & 255u) == 0u) { if (xb_ld(&(bar)[XB_TMO])) break; if (_sp > XB_SPIN_CAP) { atomicAdd(&(bar)[XB_TMO], 1u); break; } } } } while (0)
; __device__ __forceinline__ void xcd_barrier(const XcdBarrier& b) {
;     ...
;             XB_SPIN(xb_ld(&bar[XB_XGEN(b.x)]) == gen, bar);
.LBB0_437:
	global_load_dword v2, v0, s[92:93] sc1
	s_add_i32 s2, s2, 1
	s_mov_b64 s[22:23], -1
	s_waitcnt vmcnt(0)
	v_cmp_ne_u32_e32 vcc, v2, v1
	s_orn2_b64 s[16:17], vcc, exec
	s_branch .LBB0_432

; __device__ __forceinline__ unsigned xb_ld(unsigned* p)              { return __hip_atomic_load(p, __ATOMIC_RELAXED, __HIP_MEMORY_SCOPE_AGENT); }
; __device__ __forceinline__ unsigned xb_add(unsigned* p, unsigned v) { return __hip_atomic_fetch_add(p, v, __ATOMIC_RELAXED, __HIP_MEMORY_SCOPE_AGENT); }
; #define XB_SPIN(cond, bar) do { unsigned _sp = 0; while (cond) { __builtin_amdgcn_s_sleep(1); \
;     if ((++_sp & 255u) == 0u) { if (xb_ld(&(bar)[XB_TMO])) break; if (_sp > XB_SPIN_CAP) { atomicAdd(&(bar)[XB_TMO], 1u); break; } } } } while (0)
; __device__ __forceinline__ void xcd_barrier(const XcdBarrier& b) {
;     ...
;         const unsigned old = xb_add(&bar[XB_XSUB(b.x)], 1u);
;         const unsigned gen = old / nloc;
;         if (old + 1u == (gen + 1u) * nloc) {
;             __builtin_amdgcn_fence(__ATOMIC_RELEASE, "agent");
;             asm volatile("s_waitcnt vmcnt(0)" ::: "memory");
;             const unsigned og = xb_add(&bar[XB_TOP], 1u);
;             const unsigned tg = og / nx;
;             if (og + 1u == (tg + 1u) * nx) xb_add(&bar[XB_TOPGEN], 1u);
;             else XB_SPIN(xb_ld(&bar[XB_TOPGEN]) == tg, bar);
;             __builtin_amdgcn_fence(__ATOMIC_ACQUIRE, "agent");
;             xb_add(&bar[XB_XGEN(b.x)], 1u);
;             asm volatile("s_waitcnt vmcnt(0)" ::: "memory");
;         } else {
;             XB_SPIN(xb_ld(&bar[XB_XGEN(b.x)]) == gen, bar);
.LBB0_486:
	v_mov_b32_e32 v1, 1
	global_atomic_add v3, v[186:187], v1, off sc0
	v_cvt_f32_u32_e32 v1, v2
	v_sub_u32_e32 v4, 0, v2
	v_rcp_iflag_f32_e32 v1, v1
	s_nop 0
	v_mul_f32_e32 v1, 0x4f7ffffe, v1
	v_cvt_u32_f32_e32 v1, v1
	v_mul_lo_u32 v4, v4, v1
	v_mul_hi_u32 v4, v1, v4
	v_add_u32_e32 v1, v1, v4
	s_waitcnt vmcnt(0)
	v_mul_hi_u32 v1, v3, v1
	v_mul_lo_u32 v4, v1, v2
	v_sub_u32_e32 v4, v3, v4
	v_add_u32_e32 v5, 1, v1
	v_cmp_ge_u32_e32 vcc, v4, v2
	v_add_u32_e32 v3, 1, v3
	s_nop 0
	v_cndmask_b32_e32 v1, v1, v5, vcc
	v_sub_u32_e32 v5, v4, v2
	v_cndmask_b32_e32 v4, v4, v5, vcc
	v_add_u32_e32 v5, 1, v1
	v_cmp_ge_u32_e32 vcc, v4, v2
	s_nop 1
	v_cndmask_b32_e32 v1, v1, v5, vcc
	v_mul_lo_u32 v4, v2, v1
	v_add_u32_e32 v2, v4, v2
	v_cmp_ne_u32_e32 vcc, v3, v2
	s_and_saveexec_b64 s[2:3], vcc
	s_xor_b64 s[8:9], exec, s[2:3]
	s_cbranch_execz .LBB0_500
	s_waitcnt lgkmcnt(0)
	v_mov_b32_e32 v0, 0
	global_load_dword v0, v0, s[92:93] sc1
	s_waitcnt vmcnt(0)
	v_cmp_eq_u32_e32 vcc, v0, v1
	s_and_saveexec_b64 s[12:13], vcc
	s_cbranch_execz .LBB0_499
	s_mov_b32 s2, 1
	s_mov_b64 s[14:15], 0
	v_mov_b32_e32 v0, 0
	s_branch .LBB0_490

; __device__ __forceinline__ unsigned xb_ld(unsigned* p)              { return __hip_atomic_load(p, __ATOMIC_RELAXED, __HIP_MEMORY_SCOPE_AGENT); }
; #define XB_SPIN(cond, bar) do { unsigned _sp = 0; while (cond) { __builtin_amdgcn_s_sleep(1); \
;     if ((++_sp & 255u) == 0u) { if (xb_ld(&(bar)[XB_TMO])) break; if (_sp > XB_SPIN_CAP) { atomicAdd(&(bar)[XB_TMO], 1u); break; } } } } while (0)
; __device__ __forceinline__ void xcd_barrier(const XcdBarrier& b) {
;     ...
;             XB_SPIN(xb_ld(&bar[XB_XGEN(b.x)]) == gen, bar);
.LBB0_494:
	global_load_dword v2, v0, s[92:93] sc1
	s_add_i32 s2, s2, 1
	s_mov_b64 s[36:37], -1
	s_waitcnt vmcnt(0)
	v_cmp_ne_u32_e32 vcc, v2, v1
	s_orn2_b64 s[22:23], vcc, exec
	s_branch .LBB0_489

; __device__ __forceinline__ unsigned xb_ld(unsigned* p)              { return __hip_atomic_load(p, __ATOMIC_RELAXED, __HIP_MEMORY_SCOPE_AGENT); }
; #define XB_SPIN(cond, bar) do { unsigned _sp = 0; while (cond) { __builtin_amdgcn_s_sleep(1); \
;     if ((++_sp & 255u) == 0u) { if (xb_ld(&(bar)[XB_TMO])) break; if (_sp > XB_SPIN_CAP) { atomicAdd(&(bar)[XB_TMO], 1u); break; } } } } while (0)
; __device__ __forceinline__ void xcd_barrier(const XcdBarrier& b) {
;     ...
;             XB_SPIN(xb_ld(&bar[XB_XGEN(b.x)]) == gen, bar);
.LBB0_569:
	global_load_dword v2, v0, s[92:93] sc1
	s_add_i32 s2, s2, 1
	s_mov_b64 s[34:35], -1
	s_waitcnt vmcnt(0)
	v_cmp_ne_u32_e32 vcc, v2, v1
	s_orn2_b64 s[22:23], vcc, exec
	s_branch .LBB0_564

; __device__ __forceinline__ unsigned xb_ld(unsigned* p)              { return __hip_atomic_load(p, __ATOMIC_RELAXED, __HIP_MEMORY_SCOPE_AGENT); }
; #define XB_SPIN(cond, bar) do { unsigned _sp = 0; while (cond) { __builtin_amdgcn_s_sleep(1); \
;     if ((++_sp & 255u) == 0u) { if (xb_ld(&(bar)[XB_TMO])) break; if (_sp > XB_SPIN_CAP) { atomicAdd(&(bar)[XB_TMO], 1u); break; } } } } while (0)
; __device__ __forceinline__ void xcd_barrier(const XcdBarrier& b) {
;     ...
;             XB_SPIN(xb_ld(&bar[XB_XGEN(b.x)]) == gen, bar);
.LBB0_787:
	global_load_dword v2, v0, s[92:93] sc1
	s_add_i32 s2, s2, 1
	s_mov_b64 s[36:37], -1
	s_waitcnt vmcnt(0)
	v_cmp_ne_u32_e32 vcc, v2, v1
	s_orn2_b64 s[16:17], vcc, exec
	s_branch .LBB0_782

; __device__ __forceinline__ unsigned xb_ld(unsigned* p)              { return __hip_atomic_load(p, __ATOMIC_RELAXED, __HIP_MEMORY_SCOPE_AGENT); }
; __device__ __forceinline__ unsigned xb_add(unsigned* p, unsigned v) { return __hip_atomic_fetch_add(p, v, __ATOMIC_RELAXED, __HIP_MEMORY_SCOPE_AGENT); }
; #define XB_SPIN(cond, bar) do { unsigned _sp = 0; while (cond) { __builtin_amdgcn_s_sleep(1); \
;     if ((++_sp & 255u) == 0u) { if (xb_ld(&(bar)[XB_TMO])) break; if (_sp > XB_SPIN_CAP) { atomicAdd(&(bar)[XB_TMO], 1u); break; } } } } while (0)
; __device__ __forceinline__ void xcd_barrier(const XcdBarrier& b) {
;     ...
;         const unsigned old = xb_add(&bar[XB_XSUB(b.x)], 1u);
;         const unsigned gen = old / nloc;
;         if (old + 1u == (gen + 1u) * nloc) {
;             __builtin_amdgcn_fence(__ATOMIC_RELEASE, "agent");
;             asm volatile("s_waitcnt vmcnt(0)" ::: "memory");
;             const unsigned og = xb_add(&bar[XB_TOP], 1u);
;             const unsigned tg = og / nx;
;             if (og + 1u == (tg + 1u) * nx) xb_add(&bar[XB_TOPGEN], 1u);
;             else XB_SPIN(xb_ld(&bar[XB_TOPGEN]) == tg, bar);
;             __builtin_amdgcn_fence(__ATOMIC_ACQUIRE, "agent");
;             xb_add(&bar[XB_XGEN(b.x)], 1u);
;             asm volatile("s_waitcnt vmcnt(0)" ::: "memory");
;         } else {
;             XB_SPIN(xb_ld(&bar[XB_XGEN(b.x)]) == gen, bar);
.LBB0_1112:
	v_mov_b32_e32 v1, 1
	global_atomic_add v3, v[186:187], v1, off sc0
	v_cvt_f32_u32_e32 v1, v2
	v_sub_u32_e32 v4, 0, v2
	v_rcp_iflag_f32_e32 v1, v1
	s_nop 0
	v_mul_f32_e32 v1, 0x4f7ffffe, v1
	v_cvt_u32_f32_e32 v1, v1
	v_mul_lo_u32 v4, v4, v1
	v_mul_hi_u32 v4, v1, v4
	v_add_u32_e32 v1, v1, v4
	s_waitcnt vmcnt(0)
	v_mul_hi_u32 v1, v3, v1
	v_mul_lo_u32 v4, v1, v2
	v_sub_u32_e32 v4, v3, v4
	v_add_u32_e32 v5, 1, v1
	v_cmp_ge_u32_e32 vcc, v4, v2
	v_add_u32_e32 v3, 1, v3
	s_nop 0
	v_cndmask_b32_e32 v1, v1, v5, vcc
	v_sub_u32_e32 v5, v4, v2
	v_cndmask_b32_e32 v4, v4, v5, vcc
	v_add_u32_e32 v5, 1, v1
	v_cmp_ge_u32_e32 vcc, v4, v2
	s_nop 1
	v_cndmask_b32_e32 v1, v1, v5, vcc
	v_mul_lo_u32 v4, v2, v1
	v_add_u32_e32 v2, v4, v2
	v_cmp_ne_u32_e32 vcc, v3, v2
	s_and_saveexec_b64 s[2:3], vcc
	s_xor_b64 s[4:5], exec, s[2:3]
	s_cbranch_execz .LBB0_1126
	s_waitcnt lgkmcnt(0)
	v_mov_b32_e32 v0, 0
	global_load_dword v0, v0, s[92:93] sc1
	s_waitcnt vmcnt(0)
	v_cmp_eq_u32_e32 vcc, v0, v1
	s_and_saveexec_b64 s[6:7], vcc
	s_cbranch_execz .LBB0_1125
	s_mov_b32 s2, 1
	s_mov_b64 s[8:9], 0
	v_mov_b32_e32 v0, 0
	s_branch .LBB0_1116

; __device__ __forceinline__ unsigned xb_ld(unsigned* p)              { return __hip_atomic_load(p, __ATOMIC_RELAXED, __HIP_MEMORY_SCOPE_AGENT); }
; #define XB_SPIN(cond, bar) do { unsigned _sp = 0; while (cond) { __builtin_amdgcn_s_sleep(1); \
;     if ((++_sp & 255u) == 0u) { if (xb_ld(&(bar)[XB_TMO])) break; if (_sp > XB_SPIN_CAP) { atomicAdd(&(bar)[XB_TMO], 1u); break; } } } } while (0)
; __device__ __forceinline__ void xcd_barrier(const XcdBarrier& b) {
;     ...
;             XB_SPIN(xb_ld(&bar[XB_XGEN(b.x)]) == gen, bar);
.LBB0_1120:
	global_load_dword v2, v0, s[92:93] sc1
	s_add_i32 s2, s2, 1
	s_mov_b64 s[16:17], -1
	s_waitcnt vmcnt(0)
	v_cmp_ne_u32_e32 vcc, v2, v1
	s_orn2_b64 s[14:15], vcc, exec
	s_branch .LBB0_1115

; __device__ __forceinline__ unsigned xb_ld(unsigned* p)              { return __hip_atomic_load(p, __ATOMIC_RELAXED, __HIP_MEMORY_SCOPE_AGENT); }
; #define XB_SPIN(cond, bar) do { unsigned _sp = 0; while (cond) { __builtin_amdgcn_s_sleep(1); \
;     if ((++_sp & 255u) == 0u) { if (xb_ld(&(bar)[XB_TMO])) break; if (_sp > XB_SPIN_CAP) { atomicAdd(&(bar)[XB_TMO], 1u); break; } } } } while (0)
; __device__ __forceinline__ void xcd_barrier(const XcdBarrier& b) {
;     ...
;             XB_SPIN(xb_ld(&bar[XB_XGEN(b.x)]) == gen, bar);
.LBB0_1184:
	global_load_dword v2, v0, s[92:93] sc1
	s_add_i32 s2, s2, 1
	s_mov_b64 s[14:15], -1
	s_waitcnt vmcnt(0)
	v_cmp_ne_u32_e32 vcc, v2, v1
	s_orn2_b64 s[12:13], vcc, exec
	s_branch .LBB0_1179
